# v15 + P5 branch-unit epilogue rewritten: gates/mrg loads of two row-blocks in flight, counted vmcnt, kb variants split
# speedup vs baseline: 1.0082x; 1.0013x over previous
; __device__ __forceinline__ u32x4 pack8(const f32x4& v0, const f32x4& v1) { u32x4 w; w.x = cvt_pk_bf16(v0[0], v0[1]); w.y = cvt_pk_bf16(v0[2], v0[3]); w.z = cvt_pk_bf16(v1[0], v1[1]); w.w = cvt_pk_bf16(v1[2], v1[3]); return w; }
; __device__ __forceinline__ void unpack8(const u32x4& w, f32x4& v0, f32x4& v1) { v0[0] = bflo(w.x); v0[1] = bfhi(w.x); v0[2] = bflo(w.y); v0[3] = bfhi(w.y); v1[0] = bflo(w.z); v1[1] = bfhi(w.z); v1[2] = bflo(w.w); v1[3] = bfhi(w.w); }
;     __device__ __forceinline__ void operator()(const f32x4 (&acc)[2][2][4][2], const UnitX& u, int wr, int wc, int fr, int fq) const {
;         const int row0 = u.pm * BM + wr * 64 + fr, col0 = u.pn * BM + wc * 32 + 8 * fq, kb = u.kb;
;         if (u.kind == 0) {
;     ...
;                     const int row = row0 + ai * HALF + m * 16;
; #pragma unroll
;                     for (int bj = 0; bj < 2; ++bj) {
;                         const size_t idx = (size_t)row * 1024 + col0 + bj * HALF;
;                         f32x4 g0, g1; unpack8(*(const u32x4*)(gates + idx), g0, g1);
;                         f32x4 m0 = {0.f, 0.f, 0.f, 0.f}, m1 = {0.f, 0.f, 0.f, 0.f};
;                         if (kb > 0) { m0 = *(const f32x4*)(mrg + idx); m1 = *(const f32x4*)(mrg + idx + 4); }
;                         m0 += g0 * acc[ai][bj][m][0]; m1 += g1 * acc[ai][bj][m][1];
;                         if (kb < 3) { *(f32x4*)(mrg + idx) = m0; *(f32x4*)(mrg + idx + 4) = m1; }
;                         else *(u32x4*)(mb + idx) = pack8(m0, m1);
;                     }
.LBB0_908:
	v_lshl_add_u32 v140, s28, 8, v222
	v_lshl_or_b32 v142, s26, 8, v226
	s_cmp_eq_u32 s91, 0
	v_ashrrev_i32_e32 v143, 31, v142
	v_ashrrev_i32_e32 v141, 31, v140
	s_cbranch_scc1 .LBB0_911
	v_lshl_add_u32 v238, v140, 10, v142
	v_lshlrev_b32_e32 v238, 1, v238
	s_cmp_eq_u32 s89, 0
	s_cbranch_scc1 .Lp5e_A
	s_cmp_gt_i32 s89, 2
	s_cbranch_scc1 .Lp5e_C
.Lp5e_B:
	v_mov_b32_e32 v239, v238
	v_lshlrev_b32_e32 v241, 1, v239
	global_load_dwordx4 v[128:131], v239, s[50:51]
	global_load_dwordx4 v[132:135], v241, s[48:49]
	global_load_dwordx4 v[136:139], v241, s[48:49] offset:16
	global_load_dwordx4 v[140:143], v239, s[50:51] offset:256
	global_load_dwordx4 v[144:147], v241, s[48:49] offset:512
	global_load_dwordx4 v[148:151], v241, s[48:49] offset:528
	v_add_u32_e32 v240, 0x8000, v238
	v_lshlrev_b32_e32 v242, 1, v240
	global_load_dwordx4 v[152:155], v240, s[50:51]
	global_load_dwordx4 v[156:159], v242, s[48:49]
	global_load_dwordx4 v[160:163], v242, s[48:49] offset:16
	global_load_dwordx4 v[164:167], v240, s[50:51] offset:256
	global_load_dwordx4 v[168:171], v242, s[48:49] offset:512
	global_load_dwordx4 v[172:175], v242, s[48:49] offset:528
	s_waitcnt vmcnt(6)
	v_lshlrev_b32_e32 v230, 16, v128
	v_and_b32_e32 v231, 0xffff0000, v128
	v_lshlrev_b32_e32 v232, 16, v129
	v_and_b32_e32 v233, 0xffff0000, v129
	v_lshlrev_b32_e32 v234, 16, v130
	v_and_b32_e32 v235, 0xffff0000, v130
	v_lshlrev_b32_e32 v236, 16, v131
	v_and_b32_e32 v237, 0xffff0000, v131
	v_pk_fma_f32 v[132:133], v[230:231], v[124:125], v[132:133]
	v_pk_fma_f32 v[134:135], v[232:233], v[126:127], v[134:135]
	v_pk_fma_f32 v[136:137], v[234:235], v[120:121], v[136:137]
	v_pk_fma_f32 v[138:139], v[236:237], v[122:123], v[138:139]
	global_store_dwordx4 v241, v[132:135], s[48:49]
	global_store_dwordx4 v241, v[136:139], s[48:49] offset:16
	v_lshlrev_b32_e32 v230, 16, v140
	v_and_b32_e32 v231, 0xffff0000, v140
	v_lshlrev_b32_e32 v232, 16, v141
	v_and_b32_e32 v233, 0xffff0000, v141
	v_lshlrev_b32_e32 v234, 16, v142
	v_and_b32_e32 v235, 0xffff0000, v142
	v_lshlrev_b32_e32 v236, 16, v143
	v_and_b32_e32 v237, 0xffff0000, v143
	v_pk_fma_f32 v[144:145], v[230:231], v[116:117], v[144:145]
	v_pk_fma_f32 v[146:147], v[232:233], v[118:119], v[146:147]
	v_pk_fma_f32 v[148:149], v[234:235], v[112:113], v[148:149]
	v_pk_fma_f32 v[150:151], v[236:237], v[114:115], v[150:151]
	global_store_dwordx4 v241, v[144:147], s[48:49] offset:512
	global_store_dwordx4 v241, v[148:151], s[48:49] offset:528
	v_add_u32_e32 v239, 0x10000, v238
	v_lshlrev_b32_e32 v241, 1, v239
	global_load_dwordx4 v[128:131], v239, s[50:51]
	global_load_dwordx4 v[132:135], v241, s[48:49]
	global_load_dwordx4 v[136:139], v241, s[48:49] offset:16
	global_load_dwordx4 v[140:143], v239, s[50:51] offset:256
	global_load_dwordx4 v[144:147], v241, s[48:49] offset:512
	global_load_dwordx4 v[148:151], v241, s[48:49] offset:528
	s_waitcnt vmcnt(10)
	v_lshlrev_b32_e32 v230, 16, v152
	v_and_b32_e32 v231, 0xffff0000, v152
	v_lshlrev_b32_e32 v232, 16, v153
	v_and_b32_e32 v233, 0xffff0000, v153
	v_lshlrev_b32_e32 v234, 16, v154
	v_and_b32_e32 v235, 0xffff0000, v154
	v_lshlrev_b32_e32 v236, 16, v155
	v_and_b32_e32 v237, 0xffff0000, v155
	v_pk_fma_f32 v[156:157], v[230:231], v[108:109], v[156:157]
	v_pk_fma_f32 v[158:159], v[232:233], v[110:111], v[158:159]
	v_pk_fma_f32 v[160:161], v[234:235], v[104:105], v[160:161]
	v_pk_fma_f32 v[162:163], v[236:237], v[106:107], v[162:163]
	global_store_dwordx4 v242, v[156:159], s[48:49]
	global_store_dwordx4 v242, v[160:163], s[48:49] offset:16
	v_lshlrev_b32_e32 v230, 16, v164
	v_and_b32_e32 v231, 0xffff0000, v164
	v_lshlrev_b32_e32 v232, 16, v165
	v_and_b32_e32 v233, 0xffff0000, v165
	v_lshlrev_b32_e32 v234, 16, v166
	v_and_b32_e32 v235, 0xffff0000, v166
	v_lshlrev_b32_e32 v236, 16, v167
	v_and_b32_e32 v237, 0xffff0000, v167
	v_pk_fma_f32 v[168:169], v[230:231], v[100:101], v[168:169]
	v_pk_fma_f32 v[170:171], v[232:233], v[102:103], v[170:171]
	v_pk_fma_f32 v[172:173], v[234:235], v[96:97], v[172:173]
	v_pk_fma_f32 v[174:175], v[236:237], v[98:99], v[174:175]
	global_store_dwordx4 v242, v[168:171], s[48:49] offset:512
	global_store_dwordx4 v242, v[172:175], s[48:49] offset:528
	v_add_u32_e32 v240, 0x18000, v238
	v_lshlrev_b32_e32 v242, 1, v240
	global_load_dwordx4 v[152:155], v240, s[50:51]
	global_load_dwordx4 v[156:159], v242, s[48:49]
	global_load_dwordx4 v[160:163], v242, s[48:49] offset:16
	global_load_dwordx4 v[164:167], v240, s[50:51] offset:256
	global_load_dwordx4 v[168:171], v242, s[48:49] offset:512
	global_load_dwordx4 v[172:175], v242, s[48:49] offset:528
	s_waitcnt vmcnt(10)
	v_lshlrev_b32_e32 v230, 16, v128
	v_and_b32_e32 v231, 0xffff0000, v128
	v_lshlrev_b32_e32 v232, 16, v129
	v_and_b32_e32 v233, 0xffff0000, v129
	v_lshlrev_b32_e32 v234, 16, v130
	v_and_b32_e32 v235, 0xffff0000, v130
	v_lshlrev_b32_e32 v236, 16, v131
	v_and_b32_e32 v237, 0xffff0000, v131
	v_pk_fma_f32 v[132:133], v[230:231], v[92:93], v[132:133]
	v_pk_fma_f32 v[134:135], v[232:233], v[94:95], v[134:135]
	v_pk_fma_f32 v[136:137], v[234:235], v[88:89], v[136:137]
	v_pk_fma_f32 v[138:139], v[236:237], v[90:91], v[138:139]
	global_store_dwordx4 v241, v[132:135], s[48:49]
	global_store_dwordx4 v241, v[136:139], s[48:49] offset:16
	v_lshlrev_b32_e32 v230, 16, v140
	v_and_b32_e32 v231, 0xffff0000, v140
	v_lshlrev_b32_e32 v232, 16, v141
	v_and_b32_e32 v233, 0xffff0000, v141
	v_lshlrev_b32_e32 v234, 16, v142
	v_and_b32_e32 v235, 0xffff0000, v142
	v_lshlrev_b32_e32 v236, 16, v143
	v_and_b32_e32 v237, 0xffff0000, v143
	v_pk_fma_f32 v[144:145], v[230:231], v[84:85], v[144:145]
	v_pk_fma_f32 v[146:147], v[232:233], v[86:87], v[146:147]
	v_pk_fma_f32 v[148:149], v[234:235], v[80:81], v[148:149]
	v_pk_fma_f32 v[150:151], v[236:237], v[82:83], v[150:151]
	global_store_dwordx4 v241, v[144:147], s[48:49] offset:512
	global_store_dwordx4 v241, v[148:151], s[48:49] offset:528
	v_add_u32_e32 v239, 0x40000, v238
	v_lshlrev_b32_e32 v241, 1, v239
	global_load_dwordx4 v[128:131], v239, s[50:51]
	global_load_dwordx4 v[132:135], v241, s[48:49]
	global_load_dwordx4 v[136:139], v241, s[48:49] offset:16
	global_load_dwordx4 v[140:143], v239, s[50:51] offset:256
	global_load_dwordx4 v[144:147], v241, s[48:49] offset:512
	global_load_dwordx4 v[148:151], v241, s[48:49] offset:528
	s_waitcnt vmcnt(10)
; __device__ __forceinline__ u32x4 pack8(const f32x4& v0, const f32x4& v1) { u32x4 w; w.x = cvt_pk_bf16(v0[0], v0[1]); w.y = cvt_pk_bf16(v0[2], v0[3]); w.z = cvt_pk_bf16(v1[0], v1[1]); w.w = cvt_pk_bf16(v1[2], v1[3]); return w; }
; __device__ __forceinline__ void unpack8(const u32x4& w, f32x4& v0, f32x4& v1) { v0[0] = bflo(w.x); v0[1] = bfhi(w.x); v0[2] = bflo(w.y); v0[3] = bfhi(w.y); v1[0] = bflo(w.z); v1[1] = bfhi(w.z); v1[2] = bflo(w.w); v1[3] = bfhi(w.w); }
;     __device__ __forceinline__ void operator()(const f32x4 (&acc)[2][2][4][2], const UnitX& u, int wr, int wc, int fr, int fq) const {
;     ...
;                     const int row = row0 + ai * HALF + m * 16;
; #pragma unroll
;                     for (int bj = 0; bj < 2; ++bj) {
;                         const size_t idx = (size_t)row * 1024 + col0 + bj * HALF;
;                         f32x4 g0, g1; unpack8(*(const u32x4*)(gates + idx), g0, g1);
;                         f32x4 m0 = {0.f, 0.f, 0.f, 0.f}, m1 = {0.f, 0.f, 0.f, 0.f};
;                         if (kb > 0) { m0 = *(const f32x4*)(mrg + idx); m1 = *(const f32x4*)(mrg + idx + 4); }
;                         m0 += g0 * acc[ai][bj][m][0]; m1 += g1 * acc[ai][bj][m][1];
;                         if (kb < 3) { *(f32x4*)(mrg + idx) = m0; *(f32x4*)(mrg + idx + 4) = m1; }
;                         else *(u32x4*)(mb + idx) = pack8(m0, m1);
;                     }
	v_lshlrev_b32_e32 v230, 16, v152
	v_and_b32_e32 v231, 0xffff0000, v152
	v_lshlrev_b32_e32 v232, 16, v153
	v_and_b32_e32 v233, 0xffff0000, v153
	v_lshlrev_b32_e32 v234, 16, v154
	v_and_b32_e32 v235, 0xffff0000, v154
	v_lshlrev_b32_e32 v236, 16, v155
	v_and_b32_e32 v237, 0xffff0000, v155
	v_pk_fma_f32 v[156:157], v[230:231], v[76:77], v[156:157]
	v_pk_fma_f32 v[158:159], v[232:233], v[78:79], v[158:159]
	v_pk_fma_f32 v[160:161], v[234:235], v[72:73], v[160:161]
	v_pk_fma_f32 v[162:163], v[236:237], v[74:75], v[162:163]
	global_store_dwordx4 v242, v[156:159], s[48:49]
	global_store_dwordx4 v242, v[160:163], s[48:49] offset:16
	v_lshlrev_b32_e32 v230, 16, v164
	v_and_b32_e32 v231, 0xffff0000, v164
	v_lshlrev_b32_e32 v232, 16, v165
	v_and_b32_e32 v233, 0xffff0000, v165
	v_lshlrev_b32_e32 v234, 16, v166
	v_and_b32_e32 v235, 0xffff0000, v166
	v_lshlrev_b32_e32 v236, 16, v167
	v_and_b32_e32 v237, 0xffff0000, v167
	v_pk_fma_f32 v[168:169], v[230:231], v[68:69], v[168:169]
	v_pk_fma_f32 v[170:171], v[232:233], v[70:71], v[170:171]
	v_pk_fma_f32 v[172:173], v[234:235], v[64:65], v[172:173]
	v_pk_fma_f32 v[174:175], v[236:237], v[66:67], v[174:175]
	global_store_dwordx4 v242, v[168:171], s[48:49] offset:512
	global_store_dwordx4 v242, v[172:175], s[48:49] offset:528
	v_add_u32_e32 v240, 0x48000, v238
	v_lshlrev_b32_e32 v242, 1, v240
	global_load_dwordx4 v[152:155], v240, s[50:51]
	global_load_dwordx4 v[156:159], v242, s[48:49]
	global_load_dwordx4 v[160:163], v242, s[48:49] offset:16
	global_load_dwordx4 v[164:167], v240, s[50:51] offset:256
	global_load_dwordx4 v[168:171], v242, s[48:49] offset:512
	global_load_dwordx4 v[172:175], v242, s[48:49] offset:528
	s_waitcnt vmcnt(10)
	v_lshlrev_b32_e32 v230, 16, v128
	v_and_b32_e32 v231, 0xffff0000, v128
	v_lshlrev_b32_e32 v232, 16, v129
	v_and_b32_e32 v233, 0xffff0000, v129
	v_lshlrev_b32_e32 v234, 16, v130
	v_and_b32_e32 v235, 0xffff0000, v130
	v_lshlrev_b32_e32 v236, 16, v131
	v_and_b32_e32 v237, 0xffff0000, v131
	v_pk_fma_f32 v[132:133], v[230:231], v[60:61], v[132:133]
	v_pk_fma_f32 v[134:135], v[232:233], v[62:63], v[134:135]
	v_pk_fma_f32 v[136:137], v[234:235], v[56:57], v[136:137]
	v_pk_fma_f32 v[138:139], v[236:237], v[58:59], v[138:139]
	global_store_dwordx4 v241, v[132:135], s[48:49]
	global_store_dwordx4 v241, v[136:139], s[48:49] offset:16
	v_lshlrev_b32_e32 v230, 16, v140
	v_and_b32_e32 v231, 0xffff0000, v140
	v_lshlrev_b32_e32 v232, 16, v141
	v_and_b32_e32 v233, 0xffff0000, v141
	v_lshlrev_b32_e32 v234, 16, v142
	v_and_b32_e32 v235, 0xffff0000, v142
	v_lshlrev_b32_e32 v236, 16, v143
	v_and_b32_e32 v237, 0xffff0000, v143
	v_pk_fma_f32 v[144:145], v[230:231], v[52:53], v[144:145]
	v_pk_fma_f32 v[146:147], v[232:233], v[54:55], v[146:147]
	v_pk_fma_f32 v[148:149], v[234:235], v[48:49], v[148:149]
	v_pk_fma_f32 v[150:151], v[236:237], v[50:51], v[150:151]
	global_store_dwordx4 v241, v[144:147], s[48:49] offset:512
	global_store_dwordx4 v241, v[148:151], s[48:49] offset:528
	v_add_u32_e32 v239, 0x50000, v238
	v_lshlrev_b32_e32 v241, 1, v239
	global_load_dwordx4 v[128:131], v239, s[50:51]
	global_load_dwordx4 v[132:135], v241, s[48:49]
	global_load_dwordx4 v[136:139], v241, s[48:49] offset:16
	global_load_dwordx4 v[140:143], v239, s[50:51] offset:256
	global_load_dwordx4 v[144:147], v241, s[48:49] offset:512
	global_load_dwordx4 v[148:151], v241, s[48:49] offset:528
	s_waitcnt vmcnt(10)
	v_lshlrev_b32_e32 v230, 16, v152
	v_and_b32_e32 v231, 0xffff0000, v152
	v_lshlrev_b32_e32 v232, 16, v153
	v_and_b32_e32 v233, 0xffff0000, v153
	v_lshlrev_b32_e32 v234, 16, v154
	v_and_b32_e32 v235, 0xffff0000, v154
	v_lshlrev_b32_e32 v236, 16, v155
	v_and_b32_e32 v237, 0xffff0000, v155
	v_pk_fma_f32 v[156:157], v[230:231], v[44:45], v[156:157]
	v_pk_fma_f32 v[158:159], v[232:233], v[46:47], v[158:159]
	v_pk_fma_f32 v[160:161], v[234:235], v[40:41], v[160:161]
	v_pk_fma_f32 v[162:163], v[236:237], v[42:43], v[162:163]
	global_store_dwordx4 v242, v[156:159], s[48:49]
	global_store_dwordx4 v242, v[160:163], s[48:49] offset:16
	v_lshlrev_b32_e32 v230, 16, v164
	v_and_b32_e32 v231, 0xffff0000, v164
	v_lshlrev_b32_e32 v232, 16, v165
	v_and_b32_e32 v233, 0xffff0000, v165
	v_lshlrev_b32_e32 v234, 16, v166
	v_and_b32_e32 v235, 0xffff0000, v166
	v_lshlrev_b32_e32 v236, 16, v167
	v_and_b32_e32 v237, 0xffff0000, v167
	v_pk_fma_f32 v[168:169], v[230:231], v[36:37], v[168:169]
	v_pk_fma_f32 v[170:171], v[232:233], v[38:39], v[170:171]
	v_pk_fma_f32 v[172:173], v[234:235], v[32:33], v[172:173]
	v_pk_fma_f32 v[174:175], v[236:237], v[34:35], v[174:175]
	global_store_dwordx4 v242, v[168:171], s[48:49] offset:512
	global_store_dwordx4 v242, v[172:175], s[48:49] offset:528
	v_add_u32_e32 v240, 0x58000, v238
	v_lshlrev_b32_e32 v242, 1, v240
	global_load_dwordx4 v[152:155], v240, s[50:51]
	global_load_dwordx4 v[156:159], v242, s[48:49]
	global_load_dwordx4 v[160:163], v242, s[48:49] offset:16
	global_load_dwordx4 v[164:167], v240, s[50:51] offset:256
	global_load_dwordx4 v[168:171], v242, s[48:49] offset:512
	global_load_dwordx4 v[172:175], v242, s[48:49] offset:528
	s_waitcnt vmcnt(10)
; __device__ __forceinline__ u32x4 pack8(const f32x4& v0, const f32x4& v1) { u32x4 w; w.x = cvt_pk_bf16(v0[0], v0[1]); w.y = cvt_pk_bf16(v0[2], v0[3]); w.z = cvt_pk_bf16(v1[0], v1[1]); w.w = cvt_pk_bf16(v1[2], v1[3]); return w; }
; __device__ __forceinline__ void unpack8(const u32x4& w, f32x4& v0, f32x4& v1) { v0[0] = bflo(w.x); v0[1] = bfhi(w.x); v0[2] = bflo(w.y); v0[3] = bfhi(w.y); v1[0] = bflo(w.z); v1[1] = bfhi(w.z); v1[2] = bflo(w.w); v1[3] = bfhi(w.w); }
;     __device__ __forceinline__ void operator()(const f32x4 (&acc)[2][2][4][2], const UnitX& u, int wr, int wc, int fr, int fq) const {
;     ...
;                     const int row = row0 + ai * HALF + m * 16;
; #pragma unroll
;                     for (int bj = 0; bj < 2; ++bj) {
;                         const size_t idx = (size_t)row * 1024 + col0 + bj * HALF;
;                         f32x4 g0, g1; unpack8(*(const u32x4*)(gates + idx), g0, g1);
;                         f32x4 m0 = {0.f, 0.f, 0.f, 0.f}, m1 = {0.f, 0.f, 0.f, 0.f};
;                         if (kb > 0) { m0 = *(const f32x4*)(mrg + idx); m1 = *(const f32x4*)(mrg + idx + 4); }
;                         m0 += g0 * acc[ai][bj][m][0]; m1 += g1 * acc[ai][bj][m][1];
;                         if (kb < 3) { *(f32x4*)(mrg + idx) = m0; *(f32x4*)(mrg + idx + 4) = m1; }
;                         else *(u32x4*)(mb + idx) = pack8(m0, m1);
;                     }
	v_lshlrev_b32_e32 v230, 16, v128
	v_and_b32_e32 v231, 0xffff0000, v128
	v_lshlrev_b32_e32 v232, 16, v129
	v_and_b32_e32 v233, 0xffff0000, v129
	v_lshlrev_b32_e32 v234, 16, v130
	v_and_b32_e32 v235, 0xffff0000, v130
	v_lshlrev_b32_e32 v236, 16, v131
	v_and_b32_e32 v237, 0xffff0000, v131
	v_pk_fma_f32 v[132:133], v[230:231], v[28:29], v[132:133]
	v_pk_fma_f32 v[134:135], v[232:233], v[30:31], v[134:135]
	v_pk_fma_f32 v[136:137], v[234:235], v[24:25], v[136:137]
	v_pk_fma_f32 v[138:139], v[236:237], v[26:27], v[138:139]
	global_store_dwordx4 v241, v[132:135], s[48:49]
	global_store_dwordx4 v241, v[136:139], s[48:49] offset:16
	v_lshlrev_b32_e32 v230, 16, v140
	v_and_b32_e32 v231, 0xffff0000, v140
	v_lshlrev_b32_e32 v232, 16, v141
	v_and_b32_e32 v233, 0xffff0000, v141
	v_lshlrev_b32_e32 v234, 16, v142
	v_and_b32_e32 v235, 0xffff0000, v142
	v_lshlrev_b32_e32 v236, 16, v143
	v_and_b32_e32 v237, 0xffff0000, v143
	v_pk_fma_f32 v[144:145], v[230:231], v[20:21], v[144:145]
	v_pk_fma_f32 v[146:147], v[232:233], v[22:23], v[146:147]
	v_pk_fma_f32 v[148:149], v[234:235], v[16:17], v[148:149]
	v_pk_fma_f32 v[150:151], v[236:237], v[18:19], v[150:151]
	global_store_dwordx4 v241, v[144:147], s[48:49] offset:512
	global_store_dwordx4 v241, v[148:151], s[48:49] offset:528
	s_waitcnt vmcnt(4)
	v_lshlrev_b32_e32 v230, 16, v152
	v_and_b32_e32 v231, 0xffff0000, v152
	v_lshlrev_b32_e32 v232, 16, v153
	v_and_b32_e32 v233, 0xffff0000, v153
	v_lshlrev_b32_e32 v234, 16, v154
	v_and_b32_e32 v235, 0xffff0000, v154
	v_lshlrev_b32_e32 v236, 16, v155
	v_and_b32_e32 v237, 0xffff0000, v155
	v_pk_fma_f32 v[156:157], v[230:231], v[12:13], v[156:157]
	v_pk_fma_f32 v[158:159], v[232:233], v[14:15], v[158:159]
	v_pk_fma_f32 v[160:161], v[234:235], v[8:9], v[160:161]
	v_pk_fma_f32 v[162:163], v[236:237], v[10:11], v[162:163]
	global_store_dwordx4 v242, v[156:159], s[48:49]
	global_store_dwordx4 v242, v[160:163], s[48:49] offset:16
	v_lshlrev_b32_e32 v230, 16, v164
	v_and_b32_e32 v231, 0xffff0000, v164
	v_lshlrev_b32_e32 v232, 16, v165
	v_and_b32_e32 v233, 0xffff0000, v165
	v_lshlrev_b32_e32 v234, 16, v166
	v_and_b32_e32 v235, 0xffff0000, v166
	v_lshlrev_b32_e32 v236, 16, v167
	v_and_b32_e32 v237, 0xffff0000, v167
	v_pk_fma_f32 v[168:169], v[230:231], v[4:5], v[168:169]
	v_pk_fma_f32 v[170:171], v[232:233], v[6:7], v[170:171]
	v_pk_fma_f32 v[172:173], v[234:235], v[0:1], v[172:173]
	v_pk_fma_f32 v[174:175], v[236:237], v[2:3], v[174:175]
	global_store_dwordx4 v242, v[168:171], s[48:49] offset:512
	global_store_dwordx4 v242, v[172:175], s[48:49] offset:528
	s_branch .LBB0_892
.Lp5e_A:
	v_mov_b32_e32 v239, v238
	v_lshlrev_b32_e32 v241, 1, v239
	global_load_dwordx4 v[128:131], v239, s[50:51]
	global_load_dwordx4 v[140:143], v239, s[50:51] offset:256
	v_add_u32_e32 v240, 0x8000, v238
	v_lshlrev_b32_e32 v242, 1, v240
	global_load_dwordx4 v[152:155], v240, s[50:51]
	global_load_dwordx4 v[164:167], v240, s[50:51] offset:256
	s_waitcnt vmcnt(2)
	v_lshlrev_b32_e32 v230, 16, v128
	v_and_b32_e32 v231, 0xffff0000, v128
	v_lshlrev_b32_e32 v232, 16, v129
	v_and_b32_e32 v233, 0xffff0000, v129
	v_lshlrev_b32_e32 v234, 16, v130
	v_and_b32_e32 v235, 0xffff0000, v130
	v_lshlrev_b32_e32 v236, 16, v131
	v_and_b32_e32 v237, 0xffff0000, v131
	v_pk_mul_f32 v[132:133], v[230:231], v[124:125]
	v_pk_mul_f32 v[134:135], v[232:233], v[126:127]
	v_pk_mul_f32 v[136:137], v[234:235], v[120:121]
	v_pk_mul_f32 v[138:139], v[236:237], v[122:123]
	global_store_dwordx4 v241, v[132:135], s[48:49]
	global_store_dwordx4 v241, v[136:139], s[48:49] offset:16
	v_lshlrev_b32_e32 v230, 16, v140
	v_and_b32_e32 v231, 0xffff0000, v140
	v_lshlrev_b32_e32 v232, 16, v141
	v_and_b32_e32 v233, 0xffff0000, v141
	v_lshlrev_b32_e32 v234, 16, v142
	v_and_b32_e32 v235, 0xffff0000, v142
	v_lshlrev_b32_e32 v236, 16, v143
	v_and_b32_e32 v237, 0xffff0000, v143
	v_pk_mul_f32 v[144:145], v[230:231], v[116:117]
	v_pk_mul_f32 v[146:147], v[232:233], v[118:119]
	v_pk_mul_f32 v[148:149], v[234:235], v[112:113]
	v_pk_mul_f32 v[150:151], v[236:237], v[114:115]
	global_store_dwordx4 v241, v[144:147], s[48:49] offset:512
	global_store_dwordx4 v241, v[148:151], s[48:49] offset:528
	v_add_u32_e32 v239, 0x10000, v238
	v_lshlrev_b32_e32 v241, 1, v239
	global_load_dwordx4 v[128:131], v239, s[50:51]
	global_load_dwordx4 v[140:143], v239, s[50:51] offset:256
	s_waitcnt vmcnt(6)
	v_lshlrev_b32_e32 v230, 16, v152
	v_and_b32_e32 v231, 0xffff0000, v152
	v_lshlrev_b32_e32 v232, 16, v153
	v_and_b32_e32 v233, 0xffff0000, v153
	v_lshlrev_b32_e32 v234, 16, v154
	v_and_b32_e32 v235, 0xffff0000, v154
	v_lshlrev_b32_e32 v236, 16, v155
	v_and_b32_e32 v237, 0xffff0000, v155
	v_pk_mul_f32 v[156:157], v[230:231], v[108:109]
	v_pk_mul_f32 v[158:159], v[232:233], v[110:111]
	v_pk_mul_f32 v[160:161], v[234:235], v[104:105]
	v_pk_mul_f32 v[162:163], v[236:237], v[106:107]
	global_store_dwordx4 v242, v[156:159], s[48:49]
	global_store_dwordx4 v242, v[160:163], s[48:49] offset:16
	v_lshlrev_b32_e32 v230, 16, v164
	v_and_b32_e32 v231, 0xffff0000, v164
	v_lshlrev_b32_e32 v232, 16, v165
	v_and_b32_e32 v233, 0xffff0000, v165
	v_lshlrev_b32_e32 v234, 16, v166
	v_and_b32_e32 v235, 0xffff0000, v166
	v_lshlrev_b32_e32 v236, 16, v167
	v_and_b32_e32 v237, 0xffff0000, v167
	v_pk_mul_f32 v[168:169], v[230:231], v[100:101]
	v_pk_mul_f32 v[170:171], v[232:233], v[102:103]
	v_pk_mul_f32 v[172:173], v[234:235], v[96:97]
	v_pk_mul_f32 v[174:175], v[236:237], v[98:99]
	global_store_dwordx4 v242, v[168:171], s[48:49] offset:512
	global_store_dwordx4 v242, v[172:175], s[48:49] offset:528
	v_add_u32_e32 v240, 0x18000, v238
	v_lshlrev_b32_e32 v242, 1, v240
	global_load_dwordx4 v[152:155], v240, s[50:51]
	global_load_dwordx4 v[164:167], v240, s[50:51] offset:256
	s_waitcnt vmcnt(6)
; __device__ __forceinline__ u32x4 pack8(const f32x4& v0, const f32x4& v1) { u32x4 w; w.x = cvt_pk_bf16(v0[0], v0[1]); w.y = cvt_pk_bf16(v0[2], v0[3]); w.z = cvt_pk_bf16(v1[0], v1[1]); w.w = cvt_pk_bf16(v1[2], v1[3]); return w; }
; __device__ __forceinline__ void unpack8(const u32x4& w, f32x4& v0, f32x4& v1) { v0[0] = bflo(w.x); v0[1] = bfhi(w.x); v0[2] = bflo(w.y); v0[3] = bfhi(w.y); v1[0] = bflo(w.z); v1[1] = bfhi(w.z); v1[2] = bflo(w.w); v1[3] = bfhi(w.w); }
;     __device__ __forceinline__ void operator()(const f32x4 (&acc)[2][2][4][2], const UnitX& u, int wr, int wc, int fr, int fq) const {
;     ...
;                     const int row = row0 + ai * HALF + m * 16;
; #pragma unroll
;                     for (int bj = 0; bj < 2; ++bj) {
;                         const size_t idx = (size_t)row * 1024 + col0 + bj * HALF;
;                         f32x4 g0, g1; unpack8(*(const u32x4*)(gates + idx), g0, g1);
;                         f32x4 m0 = {0.f, 0.f, 0.f, 0.f}, m1 = {0.f, 0.f, 0.f, 0.f};
;                         if (kb > 0) { m0 = *(const f32x4*)(mrg + idx); m1 = *(const f32x4*)(mrg + idx + 4); }
;                         m0 += g0 * acc[ai][bj][m][0]; m1 += g1 * acc[ai][bj][m][1];
;                         if (kb < 3) { *(f32x4*)(mrg + idx) = m0; *(f32x4*)(mrg + idx + 4) = m1; }
;                         else *(u32x4*)(mb + idx) = pack8(m0, m1);
;                     }
	v_lshlrev_b32_e32 v230, 16, v128
	v_and_b32_e32 v231, 0xffff0000, v128
	v_lshlrev_b32_e32 v232, 16, v129
	v_and_b32_e32 v233, 0xffff0000, v129
	v_lshlrev_b32_e32 v234, 16, v130
	v_and_b32_e32 v235, 0xffff0000, v130
	v_lshlrev_b32_e32 v236, 16, v131
	v_and_b32_e32 v237, 0xffff0000, v131
	v_pk_mul_f32 v[132:133], v[230:231], v[92:93]
	v_pk_mul_f32 v[134:135], v[232:233], v[94:95]
	v_pk_mul_f32 v[136:137], v[234:235], v[88:89]
	v_pk_mul_f32 v[138:139], v[236:237], v[90:91]
	global_store_dwordx4 v241, v[132:135], s[48:49]
	global_store_dwordx4 v241, v[136:139], s[48:49] offset:16
	v_lshlrev_b32_e32 v230, 16, v140
	v_and_b32_e32 v231, 0xffff0000, v140
	v_lshlrev_b32_e32 v232, 16, v141
	v_and_b32_e32 v233, 0xffff0000, v141
	v_lshlrev_b32_e32 v234, 16, v142
	v_and_b32_e32 v235, 0xffff0000, v142
	v_lshlrev_b32_e32 v236, 16, v143
	v_and_b32_e32 v237, 0xffff0000, v143
	v_pk_mul_f32 v[144:145], v[230:231], v[84:85]
	v_pk_mul_f32 v[146:147], v[232:233], v[86:87]
	v_pk_mul_f32 v[148:149], v[234:235], v[80:81]
	v_pk_mul_f32 v[150:151], v[236:237], v[82:83]
	global_store_dwordx4 v241, v[144:147], s[48:49] offset:512
	global_store_dwordx4 v241, v[148:151], s[48:49] offset:528
	v_add_u32_e32 v239, 0x40000, v238
	v_lshlrev_b32_e32 v241, 1, v239
	global_load_dwordx4 v[128:131], v239, s[50:51]
	global_load_dwordx4 v[140:143], v239, s[50:51] offset:256
	s_waitcnt vmcnt(6)
	v_lshlrev_b32_e32 v230, 16, v152
	v_and_b32_e32 v231, 0xffff0000, v152
	v_lshlrev_b32_e32 v232, 16, v153
	v_and_b32_e32 v233, 0xffff0000, v153
	v_lshlrev_b32_e32 v234, 16, v154
	v_and_b32_e32 v235, 0xffff0000, v154
	v_lshlrev_b32_e32 v236, 16, v155
	v_and_b32_e32 v237, 0xffff0000, v155
	v_pk_mul_f32 v[156:157], v[230:231], v[76:77]
	v_pk_mul_f32 v[158:159], v[232:233], v[78:79]
	v_pk_mul_f32 v[160:161], v[234:235], v[72:73]
	v_pk_mul_f32 v[162:163], v[236:237], v[74:75]
	global_store_dwordx4 v242, v[156:159], s[48:49]
	global_store_dwordx4 v242, v[160:163], s[48:49] offset:16
	v_lshlrev_b32_e32 v230, 16, v164
	v_and_b32_e32 v231, 0xffff0000, v164
	v_lshlrev_b32_e32 v232, 16, v165
	v_and_b32_e32 v233, 0xffff0000, v165
	v_lshlrev_b32_e32 v234, 16, v166
	v_and_b32_e32 v235, 0xffff0000, v166
	v_lshlrev_b32_e32 v236, 16, v167
	v_and_b32_e32 v237, 0xffff0000, v167
	v_pk_mul_f32 v[168:169], v[230:231], v[68:69]
	v_pk_mul_f32 v[170:171], v[232:233], v[70:71]
	v_pk_mul_f32 v[172:173], v[234:235], v[64:65]
	v_pk_mul_f32 v[174:175], v[236:237], v[66:67]
	global_store_dwordx4 v242, v[168:171], s[48:49] offset:512
	global_store_dwordx4 v242, v[172:175], s[48:49] offset:528
	v_add_u32_e32 v240, 0x48000, v238
	v_lshlrev_b32_e32 v242, 1, v240
	global_load_dwordx4 v[152:155], v240, s[50:51]
	global_load_dwordx4 v[164:167], v240, s[50:51] offset:256
	s_waitcnt vmcnt(6)
	v_lshlrev_b32_e32 v230, 16, v128
	v_and_b32_e32 v231, 0xffff0000, v128
	v_lshlrev_b32_e32 v232, 16, v129
	v_and_b32_e32 v233, 0xffff0000, v129
	v_lshlrev_b32_e32 v234, 16, v130
	v_and_b32_e32 v235, 0xffff0000, v130
	v_lshlrev_b32_e32 v236, 16, v131
	v_and_b32_e32 v237, 0xffff0000, v131
	v_pk_mul_f32 v[132:133], v[230:231], v[60:61]
	v_pk_mul_f32 v[134:135], v[232:233], v[62:63]
	v_pk_mul_f32 v[136:137], v[234:235], v[56:57]
	v_pk_mul_f32 v[138:139], v[236:237], v[58:59]
	global_store_dwordx4 v241, v[132:135], s[48:49]
	global_store_dwordx4 v241, v[136:139], s[48:49] offset:16
	v_lshlrev_b32_e32 v230, 16, v140
	v_and_b32_e32 v231, 0xffff0000, v140
	v_lshlrev_b32_e32 v232, 16, v141
	v_and_b32_e32 v233, 0xffff0000, v141
	v_lshlrev_b32_e32 v234, 16, v142
	v_and_b32_e32 v235, 0xffff0000, v142
	v_lshlrev_b32_e32 v236, 16, v143
	v_and_b32_e32 v237, 0xffff0000, v143
	v_pk_mul_f32 v[144:145], v[230:231], v[52:53]
	v_pk_mul_f32 v[146:147], v[232:233], v[54:55]
	v_pk_mul_f32 v[148:149], v[234:235], v[48:49]
	v_pk_mul_f32 v[150:151], v[236:237], v[50:51]
	global_store_dwordx4 v241, v[144:147], s[48:49] offset:512
	global_store_dwordx4 v241, v[148:151], s[48:49] offset:528
	v_add_u32_e32 v239, 0x50000, v238
	v_lshlrev_b32_e32 v241, 1, v239
	global_load_dwordx4 v[128:131], v239, s[50:51]
	global_load_dwordx4 v[140:143], v239, s[50:51] offset:256
	s_waitcnt vmcnt(6)
	v_lshlrev_b32_e32 v230, 16, v152
	v_and_b32_e32 v231, 0xffff0000, v152
	v_lshlrev_b32_e32 v232, 16, v153
	v_and_b32_e32 v233, 0xffff0000, v153
	v_lshlrev_b32_e32 v234, 16, v154
	v_and_b32_e32 v235, 0xffff0000, v154
	v_lshlrev_b32_e32 v236, 16, v155
	v_and_b32_e32 v237, 0xffff0000, v155
	v_pk_mul_f32 v[156:157], v[230:231], v[44:45]
	v_pk_mul_f32 v[158:159], v[232:233], v[46:47]
	v_pk_mul_f32 v[160:161], v[234:235], v[40:41]
	v_pk_mul_f32 v[162:163], v[236:237], v[42:43]
	global_store_dwordx4 v242, v[156:159], s[48:49]
	global_store_dwordx4 v242, v[160:163], s[48:49] offset:16
	v_lshlrev_b32_e32 v230, 16, v164
	v_and_b32_e32 v231, 0xffff0000, v164
	v_lshlrev_b32_e32 v232, 16, v165
	v_and_b32_e32 v233, 0xffff0000, v165
	v_lshlrev_b32_e32 v234, 16, v166
	v_and_b32_e32 v235, 0xffff0000, v166
	v_lshlrev_b32_e32 v236, 16, v167
	v_and_b32_e32 v237, 0xffff0000, v167
	v_pk_mul_f32 v[168:169], v[230:231], v[36:37]
	v_pk_mul_f32 v[170:171], v[232:233], v[38:39]
	v_pk_mul_f32 v[172:173], v[234:235], v[32:33]
	v_pk_mul_f32 v[174:175], v[236:237], v[34:35]
	global_store_dwordx4 v242, v[168:171], s[48:49] offset:512
	global_store_dwordx4 v242, v[172:175], s[48:49] offset:528
	v_add_u32_e32 v240, 0x58000, v238
	v_lshlrev_b32_e32 v242, 1, v240
	global_load_dwordx4 v[152:155], v240, s[50:51]
	global_load_dwordx4 v[164:167], v240, s[50:51] offset:256
	s_waitcnt vmcnt(6)
; __device__ __forceinline__ u32x4 pack8(const f32x4& v0, const f32x4& v1) { u32x4 w; w.x = cvt_pk_bf16(v0[0], v0[1]); w.y = cvt_pk_bf16(v0[2], v0[3]); w.z = cvt_pk_bf16(v1[0], v1[1]); w.w = cvt_pk_bf16(v1[2], v1[3]); return w; }
; __device__ __forceinline__ void unpack8(const u32x4& w, f32x4& v0, f32x4& v1) { v0[0] = bflo(w.x); v0[1] = bfhi(w.x); v0[2] = bflo(w.y); v0[3] = bfhi(w.y); v1[0] = bflo(w.z); v1[1] = bfhi(w.z); v1[2] = bflo(w.w); v1[3] = bfhi(w.w); }
;     __device__ __forceinline__ void operator()(const f32x4 (&acc)[2][2][4][2], const UnitX& u, int wr, int wc, int fr, int fq) const {
;     ...
;                     const int row = row0 + ai * HALF + m * 16;
; #pragma unroll
;                     for (int bj = 0; bj < 2; ++bj) {
;                         const size_t idx = (size_t)row * 1024 + col0 + bj * HALF;
;                         f32x4 g0, g1; unpack8(*(const u32x4*)(gates + idx), g0, g1);
;                         f32x4 m0 = {0.f, 0.f, 0.f, 0.f}, m1 = {0.f, 0.f, 0.f, 0.f};
;                         if (kb > 0) { m0 = *(const f32x4*)(mrg + idx); m1 = *(const f32x4*)(mrg + idx + 4); }
;                         m0 += g0 * acc[ai][bj][m][0]; m1 += g1 * acc[ai][bj][m][1];
;                         if (kb < 3) { *(f32x4*)(mrg + idx) = m0; *(f32x4*)(mrg + idx + 4) = m1; }
;                         else *(u32x4*)(mb + idx) = pack8(m0, m1);
;                     }
	v_lshlrev_b32_e32 v230, 16, v128
	v_and_b32_e32 v231, 0xffff0000, v128
	v_lshlrev_b32_e32 v232, 16, v129
	v_and_b32_e32 v233, 0xffff0000, v129
	v_lshlrev_b32_e32 v234, 16, v130
	v_and_b32_e32 v235, 0xffff0000, v130
	v_lshlrev_b32_e32 v236, 16, v131
	v_and_b32_e32 v237, 0xffff0000, v131
	v_pk_mul_f32 v[132:133], v[230:231], v[28:29]
	v_pk_mul_f32 v[134:135], v[232:233], v[30:31]
	v_pk_mul_f32 v[136:137], v[234:235], v[24:25]
	v_pk_mul_f32 v[138:139], v[236:237], v[26:27]
	global_store_dwordx4 v241, v[132:135], s[48:49]
	global_store_dwordx4 v241, v[136:139], s[48:49] offset:16
	v_lshlrev_b32_e32 v230, 16, v140
	v_and_b32_e32 v231, 0xffff0000, v140
	v_lshlrev_b32_e32 v232, 16, v141
	v_and_b32_e32 v233, 0xffff0000, v141
	v_lshlrev_b32_e32 v234, 16, v142
	v_and_b32_e32 v235, 0xffff0000, v142
	v_lshlrev_b32_e32 v236, 16, v143
	v_and_b32_e32 v237, 0xffff0000, v143
	v_pk_mul_f32 v[144:145], v[230:231], v[20:21]
	v_pk_mul_f32 v[146:147], v[232:233], v[22:23]
	v_pk_mul_f32 v[148:149], v[234:235], v[16:17]
	v_pk_mul_f32 v[150:151], v[236:237], v[18:19]
	global_store_dwordx4 v241, v[144:147], s[48:49] offset:512
	global_store_dwordx4 v241, v[148:151], s[48:49] offset:528
	s_waitcnt vmcnt(4)
	v_lshlrev_b32_e32 v230, 16, v152
	v_and_b32_e32 v231, 0xffff0000, v152
	v_lshlrev_b32_e32 v232, 16, v153
	v_and_b32_e32 v233, 0xffff0000, v153
	v_lshlrev_b32_e32 v234, 16, v154
	v_and_b32_e32 v235, 0xffff0000, v154
	v_lshlrev_b32_e32 v236, 16, v155
	v_and_b32_e32 v237, 0xffff0000, v155
	v_pk_mul_f32 v[156:157], v[230:231], v[12:13]
	v_pk_mul_f32 v[158:159], v[232:233], v[14:15]
	v_pk_mul_f32 v[160:161], v[234:235], v[8:9]
	v_pk_mul_f32 v[162:163], v[236:237], v[10:11]
	global_store_dwordx4 v242, v[156:159], s[48:49]
	global_store_dwordx4 v242, v[160:163], s[48:49] offset:16
	v_lshlrev_b32_e32 v230, 16, v164
	v_and_b32_e32 v231, 0xffff0000, v164
	v_lshlrev_b32_e32 v232, 16, v165
	v_and_b32_e32 v233, 0xffff0000, v165
	v_lshlrev_b32_e32 v234, 16, v166
	v_and_b32_e32 v235, 0xffff0000, v166
	v_lshlrev_b32_e32 v236, 16, v167
	v_and_b32_e32 v237, 0xffff0000, v167
	v_pk_mul_f32 v[168:169], v[230:231], v[4:5]
	v_pk_mul_f32 v[170:171], v[232:233], v[6:7]
	v_pk_mul_f32 v[172:173], v[234:235], v[0:1]
	v_pk_mul_f32 v[174:175], v[236:237], v[2:3]
	global_store_dwordx4 v242, v[168:171], s[48:49] offset:512
	global_store_dwordx4 v242, v[172:175], s[48:49] offset:528
	s_branch .LBB0_892
.Lp5e_C:
	v_mov_b32_e32 v239, v238
	v_lshlrev_b32_e32 v241, 1, v239
	global_load_dwordx4 v[128:131], v239, s[50:51]
	global_load_dwordx4 v[132:135], v241, s[48:49]
	global_load_dwordx4 v[136:139], v241, s[48:49] offset:16
	global_load_dwordx4 v[140:143], v239, s[50:51] offset:256
	global_load_dwordx4 v[144:147], v241, s[48:49] offset:512
	global_load_dwordx4 v[148:151], v241, s[48:49] offset:528
	v_add_u32_e32 v240, 0x8000, v238
	v_lshlrev_b32_e32 v242, 1, v240
	global_load_dwordx4 v[152:155], v240, s[50:51]
	global_load_dwordx4 v[156:159], v242, s[48:49]
	global_load_dwordx4 v[160:163], v242, s[48:49] offset:16
	global_load_dwordx4 v[164:167], v240, s[50:51] offset:256
	global_load_dwordx4 v[168:171], v242, s[48:49] offset:512
	global_load_dwordx4 v[172:175], v242, s[48:49] offset:528
	s_waitcnt vmcnt(6)
	v_lshlrev_b32_e32 v230, 16, v128
	v_and_b32_e32 v231, 0xffff0000, v128
	v_lshlrev_b32_e32 v232, 16, v129
	v_and_b32_e32 v233, 0xffff0000, v129
	v_lshlrev_b32_e32 v234, 16, v130
	v_and_b32_e32 v235, 0xffff0000, v130
	v_lshlrev_b32_e32 v236, 16, v131
	v_and_b32_e32 v237, 0xffff0000, v131
	v_pk_fma_f32 v[132:133], v[230:231], v[124:125], v[132:133]
	v_pk_fma_f32 v[134:135], v[232:233], v[126:127], v[134:135]
	v_pk_fma_f32 v[136:137], v[234:235], v[120:121], v[136:137]
	v_pk_fma_f32 v[138:139], v[236:237], v[122:123], v[138:139]
	v_cvt_pk_bf16_f32 v128, v132, v133
	v_cvt_pk_bf16_f32 v129, v134, v135
	v_cvt_pk_bf16_f32 v130, v136, v137
	v_cvt_pk_bf16_f32 v131, v138, v139
	global_store_dwordx4 v239, v[128:131], s[52:53]
	v_lshlrev_b32_e32 v230, 16, v140
	v_and_b32_e32 v231, 0xffff0000, v140
	v_lshlrev_b32_e32 v232, 16, v141
	v_and_b32_e32 v233, 0xffff0000, v141
	v_lshlrev_b32_e32 v234, 16, v142
	v_and_b32_e32 v235, 0xffff0000, v142
	v_lshlrev_b32_e32 v236, 16, v143
	v_and_b32_e32 v237, 0xffff0000, v143
	v_pk_fma_f32 v[144:145], v[230:231], v[116:117], v[144:145]
	v_pk_fma_f32 v[146:147], v[232:233], v[118:119], v[146:147]
	v_pk_fma_f32 v[148:149], v[234:235], v[112:113], v[148:149]
	v_pk_fma_f32 v[150:151], v[236:237], v[114:115], v[150:151]
	v_cvt_pk_bf16_f32 v140, v144, v145
	v_cvt_pk_bf16_f32 v141, v146, v147
	v_cvt_pk_bf16_f32 v142, v148, v149
	v_cvt_pk_bf16_f32 v143, v150, v151
	global_store_dwordx4 v239, v[140:143], s[52:53] offset:256
	v_add_u32_e32 v239, 0x10000, v238
	v_lshlrev_b32_e32 v241, 1, v239
	global_load_dwordx4 v[128:131], v239, s[50:51]
	global_load_dwordx4 v[132:135], v241, s[48:49]
	global_load_dwordx4 v[136:139], v241, s[48:49] offset:16
	global_load_dwordx4 v[140:143], v239, s[50:51] offset:256
	global_load_dwordx4 v[144:147], v241, s[48:49] offset:512
	global_load_dwordx4 v[148:151], v241, s[48:49] offset:528
	s_waitcnt vmcnt(8)
; __device__ __forceinline__ u32x4 pack8(const f32x4& v0, const f32x4& v1) { u32x4 w; w.x = cvt_pk_bf16(v0[0], v0[1]); w.y = cvt_pk_bf16(v0[2], v0[3]); w.z = cvt_pk_bf16(v1[0], v1[1]); w.w = cvt_pk_bf16(v1[2], v1[3]); return w; }
; __device__ __forceinline__ void unpack8(const u32x4& w, f32x4& v0, f32x4& v1) { v0[0] = bflo(w.x); v0[1] = bfhi(w.x); v0[2] = bflo(w.y); v0[3] = bfhi(w.y); v1[0] = bflo(w.z); v1[1] = bfhi(w.z); v1[2] = bflo(w.w); v1[3] = bfhi(w.w); }
;     __device__ __forceinline__ void operator()(const f32x4 (&acc)[2][2][4][2], const UnitX& u, int wr, int wc, int fr, int fq) const {
;     ...
;                     const int row = row0 + ai * HALF + m * 16;
; #pragma unroll
;                     for (int bj = 0; bj < 2; ++bj) {
;                         const size_t idx = (size_t)row * 1024 + col0 + bj * HALF;
;                         f32x4 g0, g1; unpack8(*(const u32x4*)(gates + idx), g0, g1);
;                         f32x4 m0 = {0.f, 0.f, 0.f, 0.f}, m1 = {0.f, 0.f, 0.f, 0.f};
;                         if (kb > 0) { m0 = *(const f32x4*)(mrg + idx); m1 = *(const f32x4*)(mrg + idx + 4); }
;                         m0 += g0 * acc[ai][bj][m][0]; m1 += g1 * acc[ai][bj][m][1];
;                         if (kb < 3) { *(f32x4*)(mrg + idx) = m0; *(f32x4*)(mrg + idx + 4) = m1; }
;                         else *(u32x4*)(mb + idx) = pack8(m0, m1);
;                     }
	v_lshlrev_b32_e32 v230, 16, v152
	v_and_b32_e32 v231, 0xffff0000, v152
	v_lshlrev_b32_e32 v232, 16, v153
	v_and_b32_e32 v233, 0xffff0000, v153
	v_lshlrev_b32_e32 v234, 16, v154
	v_and_b32_e32 v235, 0xffff0000, v154
	v_lshlrev_b32_e32 v236, 16, v155
	v_and_b32_e32 v237, 0xffff0000, v155
	v_pk_fma_f32 v[156:157], v[230:231], v[108:109], v[156:157]
	v_pk_fma_f32 v[158:159], v[232:233], v[110:111], v[158:159]
	v_pk_fma_f32 v[160:161], v[234:235], v[104:105], v[160:161]
	v_pk_fma_f32 v[162:163], v[236:237], v[106:107], v[162:163]
	v_cvt_pk_bf16_f32 v152, v156, v157
	v_cvt_pk_bf16_f32 v153, v158, v159
	v_cvt_pk_bf16_f32 v154, v160, v161
	v_cvt_pk_bf16_f32 v155, v162, v163
	global_store_dwordx4 v240, v[152:155], s[52:53]
	v_lshlrev_b32_e32 v230, 16, v164
	v_and_b32_e32 v231, 0xffff0000, v164
	v_lshlrev_b32_e32 v232, 16, v165
	v_and_b32_e32 v233, 0xffff0000, v165
	v_lshlrev_b32_e32 v234, 16, v166
	v_and_b32_e32 v235, 0xffff0000, v166
	v_lshlrev_b32_e32 v236, 16, v167
	v_and_b32_e32 v237, 0xffff0000, v167
	v_pk_fma_f32 v[168:169], v[230:231], v[100:101], v[168:169]
	v_pk_fma_f32 v[170:171], v[232:233], v[102:103], v[170:171]
	v_pk_fma_f32 v[172:173], v[234:235], v[96:97], v[172:173]
	v_pk_fma_f32 v[174:175], v[236:237], v[98:99], v[174:175]
	v_cvt_pk_bf16_f32 v164, v168, v169
	v_cvt_pk_bf16_f32 v165, v170, v171
	v_cvt_pk_bf16_f32 v166, v172, v173
	v_cvt_pk_bf16_f32 v167, v174, v175
	global_store_dwordx4 v240, v[164:167], s[52:53] offset:256
	v_add_u32_e32 v240, 0x18000, v238
	v_lshlrev_b32_e32 v242, 1, v240
	global_load_dwordx4 v[152:155], v240, s[50:51]
	global_load_dwordx4 v[156:159], v242, s[48:49]
	global_load_dwordx4 v[160:163], v242, s[48:49] offset:16
	global_load_dwordx4 v[164:167], v240, s[50:51] offset:256
	global_load_dwordx4 v[168:171], v242, s[48:49] offset:512
	global_load_dwordx4 v[172:175], v242, s[48:49] offset:528
	s_waitcnt vmcnt(8)
	v_lshlrev_b32_e32 v230, 16, v128
	v_and_b32_e32 v231, 0xffff0000, v128
	v_lshlrev_b32_e32 v232, 16, v129
	v_and_b32_e32 v233, 0xffff0000, v129
	v_lshlrev_b32_e32 v234, 16, v130
	v_and_b32_e32 v235, 0xffff0000, v130
	v_lshlrev_b32_e32 v236, 16, v131
	v_and_b32_e32 v237, 0xffff0000, v131
	v_pk_fma_f32 v[132:133], v[230:231], v[92:93], v[132:133]
	v_pk_fma_f32 v[134:135], v[232:233], v[94:95], v[134:135]
	v_pk_fma_f32 v[136:137], v[234:235], v[88:89], v[136:137]
	v_pk_fma_f32 v[138:139], v[236:237], v[90:91], v[138:139]
	v_cvt_pk_bf16_f32 v128, v132, v133
	v_cvt_pk_bf16_f32 v129, v134, v135
	v_cvt_pk_bf16_f32 v130, v136, v137
	v_cvt_pk_bf16_f32 v131, v138, v139
	global_store_dwordx4 v239, v[128:131], s[52:53]
	v_lshlrev_b32_e32 v230, 16, v140
	v_and_b32_e32 v231, 0xffff0000, v140
	v_lshlrev_b32_e32 v232, 16, v141
	v_and_b32_e32 v233, 0xffff0000, v141
	v_lshlrev_b32_e32 v234, 16, v142
	v_and_b32_e32 v235, 0xffff0000, v142
	v_lshlrev_b32_e32 v236, 16, v143
	v_and_b32_e32 v237, 0xffff0000, v143
	v_pk_fma_f32 v[144:145], v[230:231], v[84:85], v[144:145]
	v_pk_fma_f32 v[146:147], v[232:233], v[86:87], v[146:147]
	v_pk_fma_f32 v[148:149], v[234:235], v[80:81], v[148:149]
	v_pk_fma_f32 v[150:151], v[236:237], v[82:83], v[150:151]
	v_cvt_pk_bf16_f32 v140, v144, v145
	v_cvt_pk_bf16_f32 v141, v146, v147
	v_cvt_pk_bf16_f32 v142, v148, v149
	v_cvt_pk_bf16_f32 v143, v150, v151
	global_store_dwordx4 v239, v[140:143], s[52:53] offset:256
	v_add_u32_e32 v239, 0x40000, v238
	v_lshlrev_b32_e32 v241, 1, v239
	global_load_dwordx4 v[128:131], v239, s[50:51]
	global_load_dwordx4 v[132:135], v241, s[48:49]
	global_load_dwordx4 v[136:139], v241, s[48:49] offset:16
	global_load_dwordx4 v[140:143], v239, s[50:51] offset:256
	global_load_dwordx4 v[144:147], v241, s[48:49] offset:512
	global_load_dwordx4 v[148:151], v241, s[48:49] offset:528
	s_waitcnt vmcnt(8)
	v_lshlrev_b32_e32 v230, 16, v152
	v_and_b32_e32 v231, 0xffff0000, v152
	v_lshlrev_b32_e32 v232, 16, v153
	v_and_b32_e32 v233, 0xffff0000, v153
	v_lshlrev_b32_e32 v234, 16, v154
	v_and_b32_e32 v235, 0xffff0000, v154
	v_lshlrev_b32_e32 v236, 16, v155
	v_and_b32_e32 v237, 0xffff0000, v155
	v_pk_fma_f32 v[156:157], v[230:231], v[76:77], v[156:157]
	v_pk_fma_f32 v[158:159], v[232:233], v[78:79], v[158:159]
	v_pk_fma_f32 v[160:161], v[234:235], v[72:73], v[160:161]
	v_pk_fma_f32 v[162:163], v[236:237], v[74:75], v[162:163]
	v_cvt_pk_bf16_f32 v152, v156, v157
	v_cvt_pk_bf16_f32 v153, v158, v159
	v_cvt_pk_bf16_f32 v154, v160, v161
	v_cvt_pk_bf16_f32 v155, v162, v163
	global_store_dwordx4 v240, v[152:155], s[52:53]
	v_lshlrev_b32_e32 v230, 16, v164
	v_and_b32_e32 v231, 0xffff0000, v164
	v_lshlrev_b32_e32 v232, 16, v165
	v_and_b32_e32 v233, 0xffff0000, v165
	v_lshlrev_b32_e32 v234, 16, v166
	v_and_b32_e32 v235, 0xffff0000, v166
	v_lshlrev_b32_e32 v236, 16, v167
	v_and_b32_e32 v237, 0xffff0000, v167
	v_pk_fma_f32 v[168:169], v[230:231], v[68:69], v[168:169]
	v_pk_fma_f32 v[170:171], v[232:233], v[70:71], v[170:171]
	v_pk_fma_f32 v[172:173], v[234:235], v[64:65], v[172:173]
	v_pk_fma_f32 v[174:175], v[236:237], v[66:67], v[174:175]
	v_cvt_pk_bf16_f32 v164, v168, v169
	v_cvt_pk_bf16_f32 v165, v170, v171
	v_cvt_pk_bf16_f32 v166, v172, v173
	v_cvt_pk_bf16_f32 v167, v174, v175
	global_store_dwordx4 v240, v[164:167], s[52:53] offset:256
	v_add_u32_e32 v240, 0x48000, v238
	v_lshlrev_b32_e32 v242, 1, v240
	global_load_dwordx4 v[152:155], v240, s[50:51]
	global_load_dwordx4 v[156:159], v242, s[48:49]
	global_load_dwordx4 v[160:163], v242, s[48:49] offset:16
	global_load_dwordx4 v[164:167], v240, s[50:51] offset:256
	global_load_dwordx4 v[168:171], v242, s[48:49] offset:512
	global_load_dwordx4 v[172:175], v242, s[48:49] offset:528
	s_waitcnt vmcnt(8)
; __device__ __forceinline__ u32x4 pack8(const f32x4& v0, const f32x4& v1) { u32x4 w; w.x = cvt_pk_bf16(v0[0], v0[1]); w.y = cvt_pk_bf16(v0[2], v0[3]); w.z = cvt_pk_bf16(v1[0], v1[1]); w.w = cvt_pk_bf16(v1[2], v1[3]); return w; }
; __device__ __forceinline__ void unpack8(const u32x4& w, f32x4& v0, f32x4& v1) { v0[0] = bflo(w.x); v0[1] = bfhi(w.x); v0[2] = bflo(w.y); v0[3] = bfhi(w.y); v1[0] = bflo(w.z); v1[1] = bfhi(w.z); v1[2] = bflo(w.w); v1[3] = bfhi(w.w); }
;     __device__ __forceinline__ void operator()(const f32x4 (&acc)[2][2][4][2], const UnitX& u, int wr, int wc, int fr, int fq) const {
;     ...
; #pragma unroll
;             for (int ai = 0; ai < 2; ++ai)
; #pragma unroll
;                 for (int m = 0; m < 4; ++m) {
;                     const int row = row0 + ai * HALF + m * 16;
; #pragma unroll
;                     for (int bj = 0; bj < 2; ++bj) {
;                         const size_t idx = (size_t)row * 1024 + col0 + bj * HALF;
;                         f32x4 g0, g1; unpack8(*(const u32x4*)(gates + idx), g0, g1);
;                         f32x4 m0 = {0.f, 0.f, 0.f, 0.f}, m1 = {0.f, 0.f, 0.f, 0.f};
;                         if (kb > 0) { m0 = *(const f32x4*)(mrg + idx); m1 = *(const f32x4*)(mrg + idx + 4); }
;                         m0 += g0 * acc[ai][bj][m][0]; m1 += g1 * acc[ai][bj][m][1];
;                         if (kb < 3) { *(f32x4*)(mrg + idx) = m0; *(f32x4*)(mrg + idx + 4) = m1; }
;                         else *(u32x4*)(mb + idx) = pack8(m0, m1);
;                     }
;                 }
	v_lshlrev_b32_e32 v230, 16, v128
	v_and_b32_e32 v231, 0xffff0000, v128
	v_lshlrev_b32_e32 v232, 16, v129
	v_and_b32_e32 v233, 0xffff0000, v129
	v_lshlrev_b32_e32 v234, 16, v130
	v_and_b32_e32 v235, 0xffff0000, v130
	v_lshlrev_b32_e32 v236, 16, v131
	v_and_b32_e32 v237, 0xffff0000, v131
	v_pk_fma_f32 v[132:133], v[230:231], v[60:61], v[132:133]
	v_pk_fma_f32 v[134:135], v[232:233], v[62:63], v[134:135]
	v_pk_fma_f32 v[136:137], v[234:235], v[56:57], v[136:137]
	v_pk_fma_f32 v[138:139], v[236:237], v[58:59], v[138:139]
	v_cvt_pk_bf16_f32 v128, v132, v133
	v_cvt_pk_bf16_f32 v129, v134, v135
	v_cvt_pk_bf16_f32 v130, v136, v137
	v_cvt_pk_bf16_f32 v131, v138, v139
	global_store_dwordx4 v239, v[128:131], s[52:53]
	v_lshlrev_b32_e32 v230, 16, v140
	v_and_b32_e32 v231, 0xffff0000, v140
	v_lshlrev_b32_e32 v232, 16, v141
	v_and_b32_e32 v233, 0xffff0000, v141
	v_lshlrev_b32_e32 v234, 16, v142
	v_and_b32_e32 v235, 0xffff0000, v142
	v_lshlrev_b32_e32 v236, 16, v143
	v_and_b32_e32 v237, 0xffff0000, v143
	v_pk_fma_f32 v[144:145], v[230:231], v[52:53], v[144:145]
	v_pk_fma_f32 v[146:147], v[232:233], v[54:55], v[146:147]
	v_pk_fma_f32 v[148:149], v[234:235], v[48:49], v[148:149]
	v_pk_fma_f32 v[150:151], v[236:237], v[50:51], v[150:151]
	v_cvt_pk_bf16_f32 v140, v144, v145
	v_cvt_pk_bf16_f32 v141, v146, v147
	v_cvt_pk_bf16_f32 v142, v148, v149
	v_cvt_pk_bf16_f32 v143, v150, v151
	global_store_dwordx4 v239, v[140:143], s[52:53] offset:256
	v_add_u32_e32 v239, 0x50000, v238
	v_lshlrev_b32_e32 v241, 1, v239
	global_load_dwordx4 v[128:131], v239, s[50:51]
	global_load_dwordx4 v[132:135], v241, s[48:49]
	global_load_dwordx4 v[136:139], v241, s[48:49] offset:16
	global_load_dwordx4 v[140:143], v239, s[50:51] offset:256
	global_load_dwordx4 v[144:147], v241, s[48:49] offset:512
	global_load_dwordx4 v[148:151], v241, s[48:49] offset:528
	s_waitcnt vmcnt(8)
	v_lshlrev_b32_e32 v230, 16, v152
	v_and_b32_e32 v231, 0xffff0000, v152
	v_lshlrev_b32_e32 v232, 16, v153
	v_and_b32_e32 v233, 0xffff0000, v153
	v_lshlrev_b32_e32 v234, 16, v154
	v_and_b32_e32 v235, 0xffff0000, v154
	v_lshlrev_b32_e32 v236, 16, v155
	v_and_b32_e32 v237, 0xffff0000, v155
	v_pk_fma_f32 v[156:157], v[230:231], v[44:45], v[156:157]
	v_pk_fma_f32 v[158:159], v[232:233], v[46:47], v[158:159]
	v_pk_fma_f32 v[160:161], v[234:235], v[40:41], v[160:161]
	v_pk_fma_f32 v[162:163], v[236:237], v[42:43], v[162:163]
	v_cvt_pk_bf16_f32 v152, v156, v157
	v_cvt_pk_bf16_f32 v153, v158, v159
	v_cvt_pk_bf16_f32 v154, v160, v161
	v_cvt_pk_bf16_f32 v155, v162, v163
	global_store_dwordx4 v240, v[152:155], s[52:53]
	v_lshlrev_b32_e32 v230, 16, v164
	v_and_b32_e32 v231, 0xffff0000, v164
	v_lshlrev_b32_e32 v232, 16, v165
	v_and_b32_e32 v233, 0xffff0000, v165
	v_lshlrev_b32_e32 v234, 16, v166
	v_and_b32_e32 v235, 0xffff0000, v166
	v_lshlrev_b32_e32 v236, 16, v167
	v_and_b32_e32 v237, 0xffff0000, v167
	v_pk_fma_f32 v[168:169], v[230:231], v[36:37], v[168:169]
	v_pk_fma_f32 v[170:171], v[232:233], v[38:39], v[170:171]
	v_pk_fma_f32 v[172:173], v[234:235], v[32:33], v[172:173]
	v_pk_fma_f32 v[174:175], v[236:237], v[34:35], v[174:175]
	v_cvt_pk_bf16_f32 v164, v168, v169
	v_cvt_pk_bf16_f32 v165, v170, v171
	v_cvt_pk_bf16_f32 v166, v172, v173
	v_cvt_pk_bf16_f32 v167, v174, v175
	global_store_dwordx4 v240, v[164:167], s[52:53] offset:256
	v_add_u32_e32 v240, 0x58000, v238
	v_lshlrev_b32_e32 v242, 1, v240
	global_load_dwordx4 v[152:155], v240, s[50:51]
	global_load_dwordx4 v[156:159], v242, s[48:49]
	global_load_dwordx4 v[160:163], v242, s[48:49] offset:16
	global_load_dwordx4 v[164:167], v240, s[50:51] offset:256
	global_load_dwordx4 v[168:171], v242, s[48:49] offset:512
	global_load_dwordx4 v[172:175], v242, s[48:49] offset:528
	s_waitcnt vmcnt(8)
	v_lshlrev_b32_e32 v230, 16, v128
	v_and_b32_e32 v231, 0xffff0000, v128
	v_lshlrev_b32_e32 v232, 16, v129
	v_and_b32_e32 v233, 0xffff0000, v129
	v_lshlrev_b32_e32 v234, 16, v130
	v_and_b32_e32 v235, 0xffff0000, v130
	v_lshlrev_b32_e32 v236, 16, v131
	v_and_b32_e32 v237, 0xffff0000, v131
	v_pk_fma_f32 v[132:133], v[230:231], v[28:29], v[132:133]
	v_pk_fma_f32 v[134:135], v[232:233], v[30:31], v[134:135]
	v_pk_fma_f32 v[136:137], v[234:235], v[24:25], v[136:137]
	v_pk_fma_f32 v[138:139], v[236:237], v[26:27], v[138:139]
	v_cvt_pk_bf16_f32 v128, v132, v133
	v_cvt_pk_bf16_f32 v129, v134, v135
	v_cvt_pk_bf16_f32 v130, v136, v137
	v_cvt_pk_bf16_f32 v131, v138, v139
	global_store_dwordx4 v239, v[128:131], s[52:53]
	v_lshlrev_b32_e32 v230, 16, v140
	v_and_b32_e32 v231, 0xffff0000, v140
	v_lshlrev_b32_e32 v232, 16, v141
	v_and_b32_e32 v233, 0xffff0000, v141
	v_lshlrev_b32_e32 v234, 16, v142
	v_and_b32_e32 v235, 0xffff0000, v142
	v_lshlrev_b32_e32 v236, 16, v143
	v_and_b32_e32 v237, 0xffff0000, v143
	v_pk_fma_f32 v[144:145], v[230:231], v[20:21], v[144:145]
	v_pk_fma_f32 v[146:147], v[232:233], v[22:23], v[146:147]
	v_pk_fma_f32 v[148:149], v[234:235], v[16:17], v[148:149]
	v_pk_fma_f32 v[150:151], v[236:237], v[18:19], v[150:151]
	v_cvt_pk_bf16_f32 v140, v144, v145
	v_cvt_pk_bf16_f32 v141, v146, v147
	v_cvt_pk_bf16_f32 v142, v148, v149
	v_cvt_pk_bf16_f32 v143, v150, v151
	global_store_dwordx4 v239, v[140:143], s[52:53] offset:256
	s_waitcnt vmcnt(2)
	v_lshlrev_b32_e32 v230, 16, v152
	v_and_b32_e32 v231, 0xffff0000, v152
	v_lshlrev_b32_e32 v232, 16, v153
	v_and_b32_e32 v233, 0xffff0000, v153
	v_lshlrev_b32_e32 v234, 16, v154
	v_and_b32_e32 v235, 0xffff0000, v154
	v_lshlrev_b32_e32 v236, 16, v155
	v_and_b32_e32 v237, 0xffff0000, v155
	v_pk_fma_f32 v[156:157], v[230:231], v[12:13], v[156:157]
	v_pk_fma_f32 v[158:159], v[232:233], v[14:15], v[158:159]
	v_pk_fma_f32 v[160:161], v[234:235], v[8:9], v[160:161]
	v_pk_fma_f32 v[162:163], v[236:237], v[10:11], v[162:163]
	v_cvt_pk_bf16_f32 v152, v156, v157
	v_cvt_pk_bf16_f32 v153, v158, v159
	v_cvt_pk_bf16_f32 v154, v160, v161
	v_cvt_pk_bf16_f32 v155, v162, v163
	global_store_dwordx4 v240, v[152:155], s[52:53]
	v_lshlrev_b32_e32 v230, 16, v164
	v_and_b32_e32 v231, 0xffff0000, v164
	v_lshlrev_b32_e32 v232, 16, v165
	v_and_b32_e32 v233, 0xffff0000, v165
	v_lshlrev_b32_e32 v234, 16, v166
	v_and_b32_e32 v235, 0xffff0000, v166
	v_lshlrev_b32_e32 v236, 16, v167
	v_and_b32_e32 v237, 0xffff0000, v167
	v_pk_fma_f32 v[168:169], v[230:231], v[4:5], v[168:169]
	v_pk_fma_f32 v[170:171], v[232:233], v[6:7], v[170:171]
	v_pk_fma_f32 v[172:173], v[234:235], v[0:1], v[172:173]
	v_pk_fma_f32 v[174:175], v[236:237], v[2:3], v[174:175]
	v_cvt_pk_bf16_f32 v164, v168, v169
	v_cvt_pk_bf16_f32 v165, v170, v171
	v_cvt_pk_bf16_f32 v166, v172, v173
	v_cvt_pk_bf16_f32 v167, v174, v175
	global_store_dwordx4 v240, v[164:167], s[52:53] offset:256
	s_branch .LBB0_892
.LBB0_911:
	s_cbranch_execnz .LBB0_891
	s_branch .LBB0_892
.LBB0_1023:
	s_waitcnt vmcnt(0)
	s_cmpk_gt_u32 s61, 0xff
	s_cbranch_scc1 .LBB0_1025
	s_barrier
